# P4 Kfull Toeplitz bf16 table: one wave per row, 16-B loads/stores instead of per-element 2-B stores
# speedup vs baseline: 1.0187x; 1.0051x over previous
; __device__ __forceinline__ bf16_t f2bf(float f) { return (bf16_t)(pk2(f, f) & 0xffffu); }
; __device__ __forceinline__ void phase4(const Params& P) {
;     ...
;     auto kf_val = [&](int e) -> float {
;         const int k = e & 511, n = (e >> 9) & 511, g = e >> 18;
;         const int t = n >> 4, c = n & 15, s = k >> 4, cp = k & 15;
;         const int d0 = t - s, d1 = s - t;
;         const float a0 = KD[(((0 * 32 + g) * 32 + (d0 > 0 ? d0 : 0)) * 16 + c) * 16 + cp];
;         const float a1 = KD[(((1 * 32 + g) * 32 + (d1 > 0 ? d1 : 0)) * 16 + c) * 16 + cp];
;         return (s <= t ? a0 : 0.f) + (s >= t ? a1 : 0.f);
;     };
;     auto kf_idx = [&](int e) -> size_t { const int k = e & 511, n = (e >> 9) & 511, g = e >> 18; return ((size_t)g * 512 + n) * 768 + k; };
;     {
;         constexpr int N = 32 * 512 * 512;
;         int e0 = gtid;
;         for (; e0 + 3 * gsz < N; e0 += 4 * gsz) {
;             float val[4];
; #pragma unroll
;             for (int q = 0; q < 4; ++q) val[q] = kf_val(e0 + q * gsz);
; #pragma unroll
;             for (int q = 0; q < 4; ++q) WY[kf_idx(e0 + q * gsz)] = f2bf(val[q]);
;         }
;         for (; e0 < N; e0 += gsz) WY[kf_idx(e0)] = f2bf(kf_val(e0));
;     }
.LBB0_445:
	v_lshrrev_b32_e32 v0, 1, v170
	v_and_b32_e32 v1, 1, v170
	v_lshlrev_b32_e32 v2, 4, v170
	v_lshlrev_b32_e32 v1, 5, v1
	v_readfirstlane_b32 s0, v171
	s_nop 3
	s_lshl_b32 s1, s5, 3
	s_add_u32 s0, s0, s1
.Lkf_loop:
	s_lshr_b32 s10, s0, 9
	s_bfe_u32 s11, s0, 0x50004
	s_and_b32 s12, s0, 15
	s_lshl_b32 s10, s10, 15
	s_lshl_b32 s12, s12, 6
	s_add_u32 s10, s10, s12
	s_add_u32 s10, s10, 0x4e00000
	s_add_u32 s14, s68, s10
	s_addc_u32 s15, s69, 0
	s_add_u32 s16, s14, 0x100000
	s_addc_u32 s17, s15, 0
	v_sub_u32_e32 v8, s11, v0
	v_subrev_u32_e32 v9, s11, v0
	v_max_i32_e32 v8, 0, v8
	v_max_i32_e32 v9, 0, v9
	v_lshl_add_u32 v8, v8, 10, v1
	v_lshl_add_u32 v9, v9, 10, v1
	global_load_dwordx4 v[12:15], v8, s[14:15]
	global_load_dwordx4 v[16:19], v8, s[14:15] offset:16
	global_load_dwordx4 v[20:23], v9, s[16:17]
	global_load_dwordx4 v[24:27], v9, s[16:17] offset:16
	s_add_u32 s2, s0, 0x700
	s_cmpk_lt_u32 s2, 0x4000
	s_cbranch_scc0 .Lkf_oneA
	s_lshr_b32 s18, s2, 9
	s_bfe_u32 s19, s2, 0x50004
	s_and_b32 s20, s2, 15
	s_lshl_b32 s18, s18, 15
	s_lshl_b32 s20, s20, 6
	s_add_u32 s18, s18, s20
	s_add_u32 s18, s18, 0x4e00000
	s_add_u32 s22, s68, s18
	s_addc_u32 s23, s69, 0
	s_add_u32 s24, s22, 0x100000
	s_addc_u32 s25, s23, 0
	v_sub_u32_e32 v32, s19, v0
	v_subrev_u32_e32 v33, s19, v0
	v_max_i32_e32 v32, 0, v32
	v_max_i32_e32 v33, 0, v33
	v_lshl_add_u32 v32, v32, 10, v1
	v_lshl_add_u32 v33, v33, 10, v1
	global_load_dwordx4 v[36:39], v32, s[22:23]
	global_load_dwordx4 v[40:43], v32, s[22:23] offset:16
	global_load_dwordx4 v[44:47], v33, s[24:25]
	global_load_dwordx4 v[48:51], v33, s[24:25] offset:16
	s_mov_b32 s3, 1
	s_branch .Lkf_compute
.Lkf_oneA:
	s_mov_b32 s3, 0
.Lkf_compute:
	s_cmp_eq_u32 s3, 0
	s_cbranch_scc1 .Lkf_singleA
	s_waitcnt vmcnt(4)
	v_cmp_ge_u32_e32 vcc, s11, v0
	s_nop 1
	v_cndmask_b32_e32 v12, 0, v12, vcc
	v_cndmask_b32_e32 v13, 0, v13, vcc
	v_cndmask_b32_e32 v14, 0, v14, vcc
	v_cndmask_b32_e32 v15, 0, v15, vcc
	v_cndmask_b32_e32 v16, 0, v16, vcc
	v_cndmask_b32_e32 v17, 0, v17, vcc
	v_cndmask_b32_e32 v18, 0, v18, vcc
	v_cndmask_b32_e32 v19, 0, v19, vcc
	v_cmp_le_u32_e32 vcc, s11, v0
	s_nop 1
	v_cndmask_b32_e32 v20, 0, v20, vcc
	v_cndmask_b32_e32 v21, 0, v21, vcc
	v_cndmask_b32_e32 v22, 0, v22, vcc
	v_cndmask_b32_e32 v23, 0, v23, vcc
	v_cndmask_b32_e32 v24, 0, v24, vcc
	v_cndmask_b32_e32 v25, 0, v25, vcc
	v_cndmask_b32_e32 v26, 0, v26, vcc
	v_cndmask_b32_e32 v27, 0, v27, vcc
	v_add_f32_e32 v12, v12, v20
	v_add_f32_e32 v13, v13, v21
	v_add_f32_e32 v14, v14, v22
	v_add_f32_e32 v15, v15, v23
	v_add_f32_e32 v16, v16, v24
	v_add_f32_e32 v17, v17, v25
	v_add_f32_e32 v18, v18, v26
	v_add_f32_e32 v19, v19, v27
	v_cvt_pk_bf16_f32 v12, v12, v13
	v_cvt_pk_bf16_f32 v13, v14, v15
	v_cvt_pk_bf16_f32 v14, v16, v17
	v_cvt_pk_bf16_f32 v15, v18, v19
	s_mul_i32 s10, s0, 0x600
	s_add_u32 s14, s68, s10
	s_addc_u32 s15, s69, 0
	s_add_u32 s14, s14, 0x3600000
	s_addc_u32 s15, s15, 0
	global_store_dwordx4 v2, v[12:15], s[14:15]
	s_waitcnt vmcnt(1)
	v_cmp_ge_u32_e32 vcc, s19, v0
	s_nop 1
	v_cndmask_b32_e32 v36, 0, v36, vcc
	v_cndmask_b32_e32 v37, 0, v37, vcc
	v_cndmask_b32_e32 v38, 0, v38, vcc
	v_cndmask_b32_e32 v39, 0, v39, vcc
	v_cndmask_b32_e32 v40, 0, v40, vcc
	v_cndmask_b32_e32 v41, 0, v41, vcc
	v_cndmask_b32_e32 v42, 0, v42, vcc
	v_cndmask_b32_e32 v43, 0, v43, vcc
	v_cmp_le_u32_e32 vcc, s19, v0
	s_nop 1
	v_cndmask_b32_e32 v44, 0, v44, vcc
	v_cndmask_b32_e32 v45, 0, v45, vcc
	v_cndmask_b32_e32 v46, 0, v46, vcc
	v_cndmask_b32_e32 v47, 0, v47, vcc
	v_cndmask_b32_e32 v48, 0, v48, vcc
	v_cndmask_b32_e32 v49, 0, v49, vcc
	v_cndmask_b32_e32 v50, 0, v50, vcc
	v_cndmask_b32_e32 v51, 0, v51, vcc
	v_add_f32_e32 v36, v36, v44
	v_add_f32_e32 v37, v37, v45
	v_add_f32_e32 v38, v38, v46
	v_add_f32_e32 v39, v39, v47
	v_add_f32_e32 v40, v40, v48
	v_add_f32_e32 v41, v41, v49
	v_add_f32_e32 v42, v42, v50
	v_add_f32_e32 v43, v43, v51
	v_cvt_pk_bf16_f32 v36, v36, v37
	v_cvt_pk_bf16_f32 v37, v38, v39
	v_cvt_pk_bf16_f32 v38, v40, v41
	v_cvt_pk_bf16_f32 v39, v42, v43
	s_mul_i32 s18, s2, 0x600
	s_add_u32 s22, s68, s18
	s_addc_u32 s23, s69, 0
	s_add_u32 s22, s22, 0x3600000
	s_addc_u32 s23, s23, 0
	global_store_dwordx4 v2, v[36:39], s[22:23]
	s_add_u32 s0, s0, 0xe00
	s_cmpk_lt_u32 s0, 0x4000
	s_cbranch_scc1 .Lkf_loop
	s_branch .Lkf_done
.Lkf_singleA:
	s_waitcnt vmcnt(0)
	v_cmp_ge_u32_e32 vcc, s11, v0
	s_nop 1
	v_cndmask_b32_e32 v12, 0, v12, vcc
	v_cndmask_b32_e32 v13, 0, v13, vcc
	v_cndmask_b32_e32 v14, 0, v14, vcc
	v_cndmask_b32_e32 v15, 0, v15, vcc
	v_cndmask_b32_e32 v16, 0, v16, vcc
	v_cndmask_b32_e32 v17, 0, v17, vcc
	v_cndmask_b32_e32 v18, 0, v18, vcc
	v_cndmask_b32_e32 v19, 0, v19, vcc
	v_cmp_le_u32_e32 vcc, s11, v0
	s_nop 1
	v_cndmask_b32_e32 v20, 0, v20, vcc
	v_cndmask_b32_e32 v21, 0, v21, vcc
	v_cndmask_b32_e32 v22, 0, v22, vcc
	v_cndmask_b32_e32 v23, 0, v23, vcc
	v_cndmask_b32_e32 v24, 0, v24, vcc
	v_cndmask_b32_e32 v25, 0, v25, vcc
	v_cndmask_b32_e32 v26, 0, v26, vcc
	v_cndmask_b32_e32 v27, 0, v27, vcc
	v_add_f32_e32 v12, v12, v20
	v_add_f32_e32 v13, v13, v21
	v_add_f32_e32 v14, v14, v22
	v_add_f32_e32 v15, v15, v23
	v_add_f32_e32 v16, v16, v24
	v_add_f32_e32 v17, v17, v25
	v_add_f32_e32 v18, v18, v26
	v_add_f32_e32 v19, v19, v27
	v_cvt_pk_bf16_f32 v12, v12, v13
	v_cvt_pk_bf16_f32 v13, v14, v15
	v_cvt_pk_bf16_f32 v14, v16, v17
	v_cvt_pk_bf16_f32 v15, v18, v19
	s_mul_i32 s10, s0, 0x600
	s_add_u32 s14, s68, s10
	s_addc_u32 s15, s69, 0
	s_add_u32 s14, s14, 0x3600000
	s_addc_u32 s15, s15, 0
	global_store_dwordx4 v2, v[12:15], s[14:15]
.Lkf_done:
	s_mov_b64 s[6:7], exec
